# meta_d1 (on D1's critical path for 64 blocks): its 22 operand loads issued as one batch into dead accumulator registers, one wait, then the 11 MFMAs
# speedup vs baseline: 1.0014x; 1.0014x over previous
; __device__ __forceinline__ unsigned pk2(float lo, float hi) { return pg8::cvt_pk_bf16(lo, hi); }
; __device__ __forceinline__ void meta_d1(const Params& P, LAS unsigned char* lds, int wid, int G, int lane) {
;     ...
;     for (int t = (int)blockIdx.x; t < DM / 16; t += G) {
;         const int n0 = 16 * t, k0 = wid * (DFF / NWAVES);
;         const bf16* ap = A + (size_t)fr * DFF + k0 + 8 * fq; const bf16* bp = W + (size_t)(n0 + fr) * DFF + k0 + 8 * fq;
;         f32x4 acc = (f32x4){0.f, 0.f, 0.f, 0.f};
; #pragma unroll
;         for (int k = 0; k < DFF / NWAVES; k += 32) acc = __builtin_amdgcn_mfma_f32_16x16x32_bf16(*(const bf16x8*)(bp + k), *(const bf16x8*)(ap + k), acc, 0, 0, 0);
;         part[wid * 64 + lane] = acc;
;         __syncthreads();
;         if (wid == 0) {
;             f32x4 a = part[lane];
; #pragma unroll
;             for (int w = 1; w < NWAVES; ++w) a = a + part[w * 64 + lane];
;             const f32x4 o = *(const f32x4*)(P.in[I_META] + (size_t)fr * DM + n0 + 4 * fq) + a * 0.5f;
;             u32x2 w2; w2.x = pk2(o[0], o[1]); w2.y = pk2(o[2], o[3]); *(u32x2*)(HB + (size_t)(MMAIN + fr) * DM + n0 + 4 * fq) = w2;
;             float ss = (o[0] * o[0] + o[1] * o[1]) + (o[2] * o[2] + o[3] * o[3]); ss += __shfl_xor(ss, 16); ss += __shfl_xor(ss, 32);
;             if (fq == 0) atomicAdd(ss1 + MMAIN + fr, ss);
;         }
;         __syncthreads();
.LBB0_343:
	v_add_u32_e32 v16, s0, v148
	v_mad_i64_i32 v[56:57], s[6:7], v16, s8, v[2:3]
	global_load_dwordx4 v[64:67], v[56:57], off
	global_load_dwordx4 v[68:71], v[56:57], off offset:64
	global_load_dwordx4 v[72:75], v[56:57], off offset:128
	global_load_dwordx4 v[76:79], v[56:57], off offset:192
	global_load_dwordx4 v[80:83], v[56:57], off offset:256
	global_load_dwordx4 v[84:87], v[56:57], off offset:320
	global_load_dwordx4 v[88:91], v[56:57], off offset:384
	global_load_dwordx4 v[92:95], v[56:57], off offset:448
	global_load_dwordx4 v[96:99], v[56:57], off offset:512
	global_load_dwordx4 v[100:103], v[56:57], off offset:576
	global_load_dwordx4 v[104:107], v[56:57], off offset:640
	global_load_dwordx4 v[152:155], v[0:1], off
	global_load_dwordx4 v[156:159], v[0:1], off offset:64
	global_load_dwordx4 v[160:163], v[0:1], off offset:128
	global_load_dwordx4 v[164:167], v[0:1], off offset:192
	global_load_dwordx4 v[168:171], v[0:1], off offset:256
	global_load_dwordx4 v[172:175], v[0:1], off offset:320
	global_load_dwordx4 v[176:179], v[0:1], off offset:384
	global_load_dwordx4 v[180:183], v[0:1], off offset:448
	global_load_dwordx4 v[184:187], v[0:1], off offset:512
	global_load_dwordx4 v[188:191], v[0:1], off offset:576
	global_load_dwordx4 v[192:195], v[0:1], off offset:640
	s_and_b64 vcc, exec, s[4:5]
	s_waitcnt vmcnt(0)
	v_mfma_f32_16x16x32_bf16 v[16:19], v[64:67], v[152:155], 0
	s_nop 0
	v_mfma_f32_16x16x32_bf16 v[16:19], v[68:71], v[156:159], v[16:19]
	s_nop 0
	v_mfma_f32_16x16x32_bf16 v[16:19], v[72:75], v[160:163], v[16:19]
	s_nop 0
	v_mfma_f32_16x16x32_bf16 v[16:19], v[76:79], v[164:167], v[16:19]
	s_nop 0
	v_mfma_f32_16x16x32_bf16 v[16:19], v[80:83], v[168:171], v[16:19]
	s_nop 0
	v_mfma_f32_16x16x32_bf16 v[16:19], v[84:87], v[172:175], v[16:19]
	s_nop 0
	v_mfma_f32_16x16x32_bf16 v[16:19], v[88:91], v[176:179], v[16:19]
	s_nop 0
	v_mfma_f32_16x16x32_bf16 v[16:19], v[92:95], v[180:183], v[16:19]
	s_nop 0
	v_mfma_f32_16x16x32_bf16 v[16:19], v[96:99], v[184:187], v[16:19]
	s_nop 0
	v_mfma_f32_16x16x32_bf16 v[16:19], v[100:103], v[188:191], v[16:19]
	s_nop 0
	v_mfma_f32_16x16x32_bf16 v[16:19], v[104:107], v[192:195], v[16:19]
	s_nop 7
	ds_write_b128 v11, v[16:19]
	s_waitcnt lgkmcnt(0)
	s_barrier
	s_cbranch_vccnz .LBB0_342
	s_ashr_i32 s1, s0, 31
	v_lshl_add_u64 v[16:17], s[0:1], 2, v[8:9]
	global_load_dwordx4 v[16:19], v[16:17], off
	ds_read_b128 v[20:23], v10
	ds_read_b128 v[24:27], v10 offset:1024
	ds_read_b128 v[28:31], v10 offset:2048
	ds_read_b128 v[32:35], v10 offset:3072
	ds_read_b128 v[36:39], v10 offset:4096
	ds_read_b128 v[40:43], v10 offset:5120
	ds_read_b128 v[44:47], v10 offset:6144
	ds_read_b128 v[48:51], v10 offset:7168
	s_waitcnt lgkmcnt(6)
	v_pk_add_f32 v[22:23], v[22:23], v[26:27]
	v_pk_add_f32 v[20:21], v[20:21], v[24:25]
	s_waitcnt lgkmcnt(5)
	v_pk_add_f32 v[22:23], v[22:23], v[30:31]
	v_pk_add_f32 v[20:21], v[20:21], v[28:29]
	s_waitcnt lgkmcnt(4)
	v_pk_add_f32 v[22:23], v[22:23], v[34:35]
	v_pk_add_f32 v[20:21], v[20:21], v[32:33]
	s_waitcnt lgkmcnt(3)
	v_pk_add_f32 v[22:23], v[22:23], v[38:39]
	v_pk_add_f32 v[20:21], v[20:21], v[36:37]
	s_waitcnt lgkmcnt(2)
	v_pk_add_f32 v[22:23], v[22:23], v[42:43]
	v_pk_add_f32 v[20:21], v[20:21], v[40:41]
	s_waitcnt lgkmcnt(1)
	v_pk_add_f32 v[22:23], v[22:23], v[46:47]
	v_pk_add_f32 v[20:21], v[20:21], v[44:45]
	s_waitcnt lgkmcnt(0)
	v_pk_add_f32 v[22:23], v[22:23], v[50:51]
	v_pk_add_f32 v[20:21], v[20:21], v[48:49]
	v_cmp_lt_i32_e32 vcc, v13, v14
	s_waitcnt vmcnt(0)
	v_pk_fma_f32 v[18:19], v[22:23], 0.5, v[18:19] op_sel_hi:[1,0,1]
	v_pk_fma_f32 v[20:21], v[20:21], 0.5, v[16:17] op_sel_hi:[1,0,1]
	v_mul_f32_e32 v17, v19, v19
	v_mul_f32_e32 v16, v21, v21
	v_cndmask_b32_e32 v52, v12, v13, vcc
	v_fmac_f32_e32 v16, v20, v20
	v_fmac_f32_e32 v17, v18, v18
	v_lshlrev_b32_e32 v52, 2, v52
	v_add_f32_e32 v16, v16, v17
	ds_bpermute_b32 v17, v52, v16
	v_cmp_lt_i32_e32 vcc, v15, v14
	v_cvt_pk_bf16_f32 v20, v20, v21
	v_cvt_pk_bf16_f32 v21, v18, v19
	v_cndmask_b32_e32 v22, v12, v15, vcc
	s_waitcnt lgkmcnt(0)
	v_add_f32_e32 v16, v16, v17
	v_lshlrev_b32_e32 v17, 2, v22
	ds_bpermute_b32 v17, v17, v16
	v_lshl_add_u64 v[18:19], s[0:1], 1, v[4:5]
	global_store_dwordx2 v[18:19], v[20:21], off
	s_and_saveexec_b64 s[6:7], s[2:3]
	s_cbranch_execz .LBB0_341
	s_waitcnt lgkmcnt(0)
	v_add_f32_e32 v16, v16, v17
	global_atomic_add_f32 v[6:7], v16, off
	s_branch .LBB0_341
